# hg_local: second wave of each SIMD starts ~1.5us later so that its load waits fall in the partner's compute, on top of v91
# speedup vs baseline: 1.0146x; 1.0146x over previous
.LBB0_272:
	s_andn2_b64 vcc, exec, s[24:25]
	s_cbranch_vccnz .LBB0_475
	v_mov_b32_e32 v3, v201
	v_readlane_b32 s3, v254, 63
	v_readfirstlane_b32 s25, v3
	s_ashr_i32 s24, s25, 7
	s_add_i32 s3, s3, s24
	s_mov_b64 s[38:39], s[66:67]
	s_cmpk_gt_i32 s3, 0x3ff
	s_cbranch_scc1 .LBB0_280
	s_cmpk_lt_u32 s25, 0x100
	s_cbranch_scc1 .Lstg_hgl
	s_sleep 47
.Lstg_hgl:
	s_load_dwordx2 s[28:29], s[38:39], 0x88
	s_ashr_i32 s25, s25, 6
	s_and_b32 s44, s25, 1
	v_and_b32_e32 v0, 63, v3
	s_mulk_i32 s25, 0x4300
	s_waitcnt lgkmcnt(0)
	s_add_u32 s45, s28, 0xa000000
	s_addc_u32 s46, s29, 0
	s_add_u32 s47, s28, 0x15000000
	s_addc_u32 s48, s29, 0
	s_add_u32 s40, s28, 0x1b000000
	v_lshlrev_b32_e32 v6, 4, v0
	v_and_b32_e32 v5, 15, v3
	s_addc_u32 s41, s29, 0
	s_add_i32 s25, s25, 0
	s_lshl_b32 s26, s44, 8
	v_and_b32_e32 v11, 0x300, v6
	s_cmp_eq_u32 s44, 0
	v_and_b32_e32 v3, 48, v3
	v_or_b32_e32 v15, 16, v5
	v_or_b32_e32 v17, 32, v5
	v_or_b32_e32 v19, 48, v5
	v_or_b32_e32 v21, 0x400, v11
	v_or_b32_e32 v23, 0x440, v11
	v_or_b32_e32 v25, 0x480, v11
	s_cselect_b64 s[42:43], -1, 0
	v_lshl_add_u32 v1, v0, 6, s25
	v_add_u32_e32 v3, s25, v3
	s_movk_i32 s25, 0x3c0
	v_or_b32_e32 v8, v21, v5
	v_or_b32_e32 v10, v23, v5
	v_or_b32_e32 v12, v25, v5
	v_or_b32_e32 v16, v21, v15
	v_or_b32_e32 v18, v23, v15
	v_or_b32_e32 v20, v25, v15
	v_or_b32_e32 v22, v21, v17
	v_or_b32_e32 v24, v23, v17
	v_or_b32_e32 v26, v25, v17
	v_or_b32_e32 v28, v21, v19
	v_or_b32_e32 v30, v23, v19
	v_or_b32_e32 v32, v25, v19
	v_or_b32_e32 v21, 0x800, v11
	v_or_b32_e32 v23, 0x840, v11
	v_or_b32_e32 v25, 0x880, v11
	s_and_b64 s[28:29], s[42:43], exec
	v_and_or_b32 v13, v6, s25, v5
	v_or_b32_e32 v34, v21, v5
	v_or_b32_e32 v36, v23, v5
	v_or_b32_e32 v38, v25, v5
	v_or_b32_e32 v42, v21, v15
	v_or_b32_e32 v44, v23, v15
	v_or_b32_e32 v46, v25, v15
	v_or_b32_e32 v48, v21, v17
	v_or_b32_e32 v50, v23, v17
	v_or_b32_e32 v52, v25, v17
	v_or_b32_e32 v54, v21, v19
	v_or_b32_e32 v56, v23, v19
	v_or_b32_e32 v58, v25, v19
	v_or_b32_e32 v21, 0xc00, v11
	v_or_b32_e32 v23, 0xc40, v11
	v_or_b32_e32 v25, 0xc80, v11
	s_cselect_b32 s49, 56, 64
	v_mul_i32_i24_e32 v7, 0xffffffc4, v0
	v_lshlrev_b32_e32 v9, 6, v5
	v_or_b32_e32 v4, v11, v5
	v_or_b32_e32 v6, 0xc0, v13
	v_or_b32_e32 v14, 0x4c0, v13
	v_or_b32_e32 v40, 0x8c0, v13
	v_or_b32_e32 v60, v21, v5
	v_or_b32_e32 v62, v23, v5
	v_or_b32_e32 v64, v25, v5
	v_or_b32_e32 v66, 0xcc0, v13
	v_or_b32_e32 v68, v21, v15
	v_or_b32_e32 v70, v23, v15
	v_or_b32_e32 v72, v25, v15
	v_or_b32_e32 v74, v21, v17
	v_or_b32_e32 v78, v23, v17
	v_or_b32_e32 v80, v25, v17
	v_or_b32_e32 v82, v21, v19
	v_or_b32_e32 v84, v23, v19
	v_or_b32_e32 v86, v25, v19
	s_cselect_b32 s50, 1, -1
	v_or_b32_e32 v88, v11, v15
	v_or_b32_e32 v90, v11, v17
	v_or_b32_e32 v92, v11, v19
	s_lshl_b32 s24, s24, 7
	v_readlane_b32 s25, v255, 20
	s_add_i32 s51, s25, s24
	v_lshlrev_b32_e32 v76, 1, v0
	s_lshl_b32 s26, s26, 1
	s_waitcnt vmcnt(0)
	v_add_u32_e32 v96, v1, v7
	v_add_u32_e32 v97, v3, v9
	v_lshlrev_b32_e32 v98, 2, v4
	v_lshlrev_b32_e32 v99, 2, v6
	v_lshlrev_b32_e32 v100, 2, v88
	v_lshlrev_b32_e32 v101, 2, v90
	v_lshlrev_b32_e32 v102, 2, v92
	v_lshlrev_b32_e32 v103, 2, v8
	v_lshlrev_b32_e32 v104, 2, v10
	v_lshlrev_b32_e32 v105, 2, v12
	v_lshlrev_b32_e32 v106, 2, v14
	v_lshlrev_b32_e32 v107, 2, v16
	v_lshlrev_b32_e32 v108, 2, v18
	v_lshlrev_b32_e32 v109, 2, v20
	v_lshlrev_b32_e32 v110, 2, v22
	v_lshlrev_b32_e32 v111, 2, v24
	v_lshlrev_b32_e32 v112, 2, v26
	v_lshlrev_b32_e32 v113, 2, v28
	v_lshlrev_b32_e32 v114, 2, v30
	v_lshlrev_b32_e32 v115, 2, v32
	v_lshlrev_b32_e32 v116, 2, v34
	v_lshlrev_b32_e32 v117, 2, v36
	v_lshlrev_b32_e32 v118, 2, v38
	v_lshlrev_b32_e32 v119, 2, v40
	v_lshlrev_b32_e32 v120, 2, v42
	v_lshlrev_b32_e32 v121, 2, v44
	v_lshlrev_b32_e32 v122, 2, v46
	v_lshlrev_b32_e32 v123, 2, v48
	v_lshlrev_b32_e32 v124, 2, v50
	v_lshlrev_b32_e32 v125, 2, v52
	v_lshlrev_b32_e32 v126, 2, v54
	v_lshlrev_b32_e32 v127, 2, v56
	v_lshlrev_b32_e32 v128, 2, v58
	v_lshlrev_b32_e32 v129, 2, v60
	v_lshlrev_b32_e32 v130, 2, v62
	v_lshlrev_b32_e32 v131, 2, v64
	v_lshlrev_b32_e32 v132, 2, v66
	v_lshlrev_b32_e32 v133, 2, v68
	v_lshlrev_b32_e32 v134, 2, v70
	v_lshlrev_b32_e32 v135, 2, v72
	v_lshlrev_b32_e32 v136, 2, v74
	v_lshlrev_b32_e32 v137, 2, v78
	v_lshlrev_b32_e32 v138, 2, v80
	v_lshlrev_b32_e32 v139, 2, v82
	v_lshlrev_b32_e32 v140, 2, v84
	v_lshlrev_b32_e32 v141, 2, v86
